# attention QK double-buffer + PV 6-deep V-fragment prefetch, plus gla_post staging loads (Q/K/V pieces) issued up front into free VGPRs instead of load-wait-store chains
# baseline (speedup 1.0000x reference)
; #define LAS __attribute__((address_space(3)))
; __device__ __forceinline__ unsigned cvtpk(float lo, float hi) { return pg8::cvt_pk_bf16(lo, hi); }
; __device__ __forceinline__ float bflo(unsigned u) { return __uint_as_float(u << 16); }
; __device__ __forceinline__ float bfhi(unsigned u) { return __uint_as_float(u & 0xffff0000u); }
; __device__ __forceinline__ void gla_post_phase(LAS unsigned char* lds, const bf16_t* QT, const bf16_t* KT  , const float* DEC, const bf16_t* proj, const bf16_t* OI, const float* gnorm, bf16_t* OG, int wg, int nwg, int tid) {
;     ...
;         float idc[8];
;         { const float* dp = DEC + (size_t)bc * GLA_DK + h * 256 + (tid & 31) * 8; const f32x4 d0 = *(const f32x4*)dp, d1 = *(const f32x4*)(dp + 4);
;           idc[0] = 1.0f / d0[0]; idc[1] = 1.0f / d0[1]; idc[2] = 1.0f / d0[2]; idc[3] = 1.0f / d0[3]; idc[4] = 1.0f / d1[0]; idc[5] = 1.0f / d1[1]; idc[6] = 1.0f / d1[2]; idc[7] = 1.0f / d1[3]; }
; #pragma unroll
;         for (int i = 0; i < 4; ++i) { const int id = tid + 512 * i, row = id >> 5, ch = id & 31;
;             const u32x4 qv = *(const u32x4*)(QT + (t0 + row) * GLA_DK + h * 256 + ch * 8);
;             u32x4 qs; qs.x = cvtpk(bflo(qv.x) * idc[0], bfhi(qv.x) * idc[1]); qs.y = cvtpk(bflo(qv.y) * idc[2], bfhi(qv.y) * idc[3]);
;             qs.z = cvtpk(bflo(qv.z) * idc[4], bfhi(qv.z) * idc[5]); qs.w = cvtpk(bflo(qv.w) * idc[6], bfhi(qv.w) * idc[7]);
;             *(LAS u32x4*)(Qt + row * QP + ch * 8) = qs;
;             *(LAS u32x4*)(Kt + row * QP + ch * 8) = *(const u32x4*)(KT + (t0 + row) * GLA_DK + h * 256 + ch * 8); }
; #pragma unroll
;         for (int i = 0; i < 8; ++i) { const int id = tid + 512 * i, row = id >> 6, ch = id & 63;
;             *(LAS u32x4*)(V + row * VP + ch * 8) = *(const u32x4*)(proj + (t0 + row) * GLA_PP + 2048 + h * 512 + ch * 8); }
.LBB0_927:
	s_ashr_i32 s0, s66, 2
	s_ashr_i32 s1, s0, 31
	s_and_b32 s20, s66, 3
	s_lshl_b64 s[60:61], s[0:1], 6
	s_lshl_b64 s[0:1], s[0:1], 12
	v_readlane_b32 s30, v252, 50
	v_readlane_b32 s31, v252, 51
	s_add_u32 s6, s30, s0
	s_addc_u32 s21, s31, s1
	s_lshl_b32 s0, s20, 10
	s_add_u32 s34, s6, s0
	s_addc_u32 s35, s21, 0
	global_load_dwordx4 v[10:13], v97, s[34:35] offset:16
	global_load_dwordx4 v[6:9], v97, s[34:35]
	s_lshl_b32 s6, s20, 9
	v_lshl_add_u64 v[14:15], s[60:61], 0, v[64:65]
	v_lshl_add_u64 v[4:5], v[60:61], 0, s[6:7]
	v_lshlrev_b64 v[14:15], 11, v[14:15]
	v_lshl_add_u64 v[16:17], v[4:5], 0, v[14:15]
	s_mov_b64 s[100:101], 0x4000000
	v_lshl_add_u64 v[198:199], v[16:17], 0, s[100:101]
	global_load_dwordx4 v[212:215], v[198:199], off
	s_mov_b64 s[100:101], 0x8000
	v_lshl_add_u64 v[198:199], v[16:17], 0, s[100:101]
	global_load_dwordx4 v[200:203], v[198:199], off
	s_mov_b64 s[100:101], 0x4008000
	v_lshl_add_u64 v[198:199], v[16:17], 0, s[100:101]
	global_load_dwordx4 v[216:219], v[198:199], off
	s_mov_b64 s[100:101], 0x10000
	v_lshl_add_u64 v[198:199], v[16:17], 0, s[100:101]
	global_load_dwordx4 v[204:207], v[198:199], off
	s_mov_b64 s[100:101], 0x4010000
	v_lshl_add_u64 v[198:199], v[16:17], 0, s[100:101]
	global_load_dwordx4 v[220:223], v[198:199], off
	s_mov_b64 s[100:101], 0x18000
	v_lshl_add_u64 v[198:199], v[16:17], 0, s[100:101]
	global_load_dwordx4 v[208:211], v[198:199], off
	s_mov_b64 s[100:101], 0x4018000
	v_lshl_add_u64 v[198:199], v[16:17], 0, s[100:101]
	global_load_dwordx4 v[224:227], v[198:199], off
	s_ashr_i32 s100, s66, 2
	s_mul_i32 s100, s100, 0xc0000
	s_and_b32 s101, s66, 3
	s_lshl_b32 s101, s101, 10
	s_add_i32 s100, s100, s101
	s_add_u32 s100, s100, 0x1ac01000
	s_add_u32 s100, s100, s90
	s_addc_u32 s101, s91, 0
	v_lshrrev_b32_e32 v198, 6, v175
	v_and_b32_e32 v199, 63, v175
	v_mul_u32_u24_e32 v198, 0x3000, v198
	v_lshl_add_u32 v198, v199, 4, v198
	global_load_dwordx4 v[228:231], v198, s[100:101]
	s_add_u32 s100, s100, 0x18000
	s_addc_u32 s101, s101, 0
	global_load_dwordx4 v[232:235], v198, s[100:101]
	s_add_u32 s100, s100, 0x18000
	s_addc_u32 s101, s101, 0
	global_load_dwordx4 v[236:239], v198, s[100:101]
	s_add_u32 s100, s100, 0x18000
	s_addc_u32 s101, s101, 0
	global_load_dwordx4 v[240:243], v198, s[100:101]
	s_add_u32 s100, s100, 0x18000
	s_addc_u32 s101, s101, 0
	global_load_dwordx4 v[244:247], v198, s[100:101]
	s_add_u32 s100, s100, 0x18000
	s_addc_u32 s101, s101, 0
	global_load_dwordx4 v[248:251], v198, s[100:101]
	global_load_dwordx4 v[16:19], v[16:17], off
	v_lshl_add_u64 v[2:3], v[62:63], 0, s[6:7]
	v_lshl_add_u64 v[14:15], v[2:3], 0, v[14:15]
	s_mov_b32 s1, s7
	s_movk_i32 s21, 0x1000
	s_waitcnt vmcnt(0)
	v_div_scale_f32 v20, s[34:35], v7, v7, 1.0
	v_rcp_f32_e32 v21, v20
	s_nop 0
	v_fma_f32 v22, -v20, v21, 1.0
	v_fmac_f32_e32 v21, v22, v21
	v_div_scale_f32 v22, vcc, 1.0, v7, 1.0
	v_mul_f32_e32 v23, v22, v21
	v_fma_f32 v24, -v20, v23, v22
	v_fmac_f32_e32 v23, v24, v21
	v_fma_f32 v20, -v20, v23, v22
	v_div_fmas_f32 v20, v20, v21, v23
	v_div_fixup_f32 v7, v20, v7, 1.0
	v_div_scale_f32 v20, s[34:35], v6, v6, 1.0
	v_rcp_f32_e32 v21, v20
	s_nop 0
	v_fma_f32 v22, -v20, v21, 1.0
	v_fmac_f32_e32 v21, v22, v21
	v_div_scale_f32 v22, vcc, 1.0, v6, 1.0
	v_mul_f32_e32 v23, v22, v21
	v_fma_f32 v24, -v20, v23, v22
	v_fmac_f32_e32 v23, v24, v21
	v_fma_f32 v20, -v20, v23, v22
	v_div_fmas_f32 v20, v20, v21, v23
	v_div_fixup_f32 v6, v20, v6, 1.0
	v_lshlrev_b32_e32 v20, 16, v16
	v_and_b32_e32 v21, 0xffff0000, v16
	v_pk_mul_f32 v[20:21], v[6:7], v[20:21]
	s_nop 0
	v_cvt_pk_bf16_f32 v16, v20, v21
	v_div_scale_f32 v20, s[34:35], v9, v9, 1.0
	v_rcp_f32_e32 v21, v20
	s_nop 0
	v_fma_f32 v22, -v20, v21, 1.0
	v_fmac_f32_e32 v21, v22, v21
	v_div_scale_f32 v22, vcc, 1.0, v9, 1.0
	v_mul_f32_e32 v23, v22, v21
	v_fma_f32 v24, -v20, v23, v22
	v_fmac_f32_e32 v23, v24, v21
	v_fma_f32 v20, -v20, v23, v22
	v_div_fmas_f32 v20, v20, v21, v23
	v_div_fixup_f32 v9, v20, v9, 1.0
	v_div_scale_f32 v20, s[34:35], v8, v8, 1.0
	v_rcp_f32_e32 v21, v20
	s_nop 0
	v_fma_f32 v22, -v20, v21, 1.0
	v_fmac_f32_e32 v21, v22, v21
	v_div_scale_f32 v22, vcc, 1.0, v8, 1.0
	v_mul_f32_e32 v23, v22, v21
	v_fma_f32 v24, -v20, v23, v22
	v_fmac_f32_e32 v23, v24, v21
	v_fma_f32 v20, -v20, v23, v22
	v_div_fmas_f32 v20, v20, v21, v23
	v_div_fixup_f32 v8, v20, v8, 1.0
	v_lshlrev_b32_e32 v20, 16, v17
	v_and_b32_e32 v21, 0xffff0000, v17
	v_pk_mul_f32 v[20:21], v[8:9], v[20:21]
	s_nop 0
	v_cvt_pk_bf16_f32 v17, v20, v21
	v_div_scale_f32 v20, s[34:35], v11, v11, 1.0
	v_rcp_f32_e32 v21, v20
	s_nop 0
	v_fma_f32 v22, -v20, v21, 1.0
	v_fmac_f32_e32 v21, v22, v21
	v_div_scale_f32 v22, vcc, 1.0, v11, 1.0
	v_mul_f32_e32 v23, v22, v21
	v_fma_f32 v24, -v20, v23, v22
	v_fmac_f32_e32 v23, v24, v21
	v_fma_f32 v20, -v20, v23, v22
	v_div_fmas_f32 v20, v20, v21, v23
	v_div_fixup_f32 v11, v20, v11, 1.0
	v_div_scale_f32 v20, s[34:35], v10, v10, 1.0
	v_rcp_f32_e32 v21, v20
	s_nop 0
	v_fma_f32 v22, -v20, v21, 1.0
	v_fmac_f32_e32 v21, v22, v21
	v_div_scale_f32 v22, vcc, 1.0, v10, 1.0
	v_mul_f32_e32 v23, v22, v21
	v_fma_f32 v24, -v20, v23, v22
	v_fmac_f32_e32 v23, v24, v21
	v_fma_f32 v20, -v20, v23, v22
	v_div_fmas_f32 v20, v20, v21, v23
	v_div_fixup_f32 v10, v20, v10, 1.0
	v_lshlrev_b32_e32 v20, 16, v18
	v_and_b32_e32 v21, 0xffff0000, v18
	v_pk_mul_f32 v[20:21], v[10:11], v[20:21]
	s_nop 0
	v_cvt_pk_bf16_f32 v18, v20, v21
	v_div_scale_f32 v20, s[34:35], v13, v13, 1.0
	v_rcp_f32_e32 v21, v20
	s_nop 0
	v_fma_f32 v22, -v20, v21, 1.0
	v_fmac_f32_e32 v21, v22, v21
	v_div_scale_f32 v22, vcc, 1.0, v13, 1.0
	v_mul_f32_e32 v23, v22, v21
	v_fma_f32 v24, -v20, v23, v22
	v_fmac_f32_e32 v23, v24, v21
	v_fma_f32 v20, -v20, v23, v22
	v_div_fmas_f32 v20, v20, v21, v23
	v_div_fixup_f32 v13, v20, v13, 1.0
	v_div_scale_f32 v20, s[34:35], v12, v12, 1.0
	v_rcp_f32_e32 v21, v20
	s_nop 0
	v_fma_f32 v22, -v20, v21, 1.0
	v_fmac_f32_e32 v21, v22, v21
	v_div_scale_f32 v22, vcc, 1.0, v12, 1.0
	v_mul_f32_e32 v23, v22, v21
	v_fma_f32 v24, -v20, v23, v22
	v_fmac_f32_e32 v23, v24, v21
	v_fma_f32 v20, -v20, v23, v22
	v_div_fmas_f32 v20, v20, v21, v23
	v_div_fixup_f32 v12, v20, v12, 1.0
	v_lshlrev_b32_e32 v20, 16, v19
	v_and_b32_e32 v21, 0xffff0000, v19
	v_pk_mul_f32 v[20:21], v[12:13], v[20:21]
	s_nop 0
	v_cvt_pk_bf16_f32 v19, v20, v21
	ds_write_b128 v66, v[16:19]
	v_mov_b64_e32 v[14:15], v[212:213]
	v_mov_b64_e32 v[16:17], v[214:215]
	s_waitcnt vmcnt(0)
; #define LAS __attribute__((address_space(3)))
; __device__ __forceinline__ unsigned cvtpk(float lo, float hi) { return pg8::cvt_pk_bf16(lo, hi); }
; __device__ __forceinline__ float bflo(unsigned u) { return __uint_as_float(u << 16); }
; __device__ __forceinline__ float bfhi(unsigned u) { return __uint_as_float(u & 0xffff0000u); }
; __device__ __forceinline__ void gla_post_phase(LAS unsigned char* lds, const bf16_t* QT, const bf16_t* KT  , const float* DEC, const bf16_t* proj, const bf16_t* OI, const float* gnorm, bf16_t* OG, int wg, int nwg, int tid) {
;     ...
;         for (int i = 0; i < 4; ++i) { const int id = tid + 512 * i, row = id >> 5, ch = id & 31;
;             const u32x4 qv = *(const u32x4*)(QT + (t0 + row) * GLA_DK + h * 256 + ch * 8);
;             u32x4 qs; qs.x = cvtpk(bflo(qv.x) * idc[0], bfhi(qv.x) * idc[1]); qs.y = cvtpk(bflo(qv.y) * idc[2], bfhi(qv.y) * idc[3]);
;             qs.z = cvtpk(bflo(qv.z) * idc[4], bfhi(qv.z) * idc[5]); qs.w = cvtpk(bflo(qv.w) * idc[6], bfhi(qv.w) * idc[7]);
;             *(LAS u32x4*)(Qt + row * QP + ch * 8) = qs;
;             *(LAS u32x4*)(Kt + row * QP + ch * 8) = *(const u32x4*)(KT + (t0 + row) * GLA_DK + h * 256 + ch * 8); }
; #pragma unroll
;         for (int i = 0; i < 8; ++i) { const int id = tid + 512 * i, row = id >> 6, ch = id & 63;
;             *(LAS u32x4*)(V + row * VP + ch * 8) = *(const u32x4*)(proj + (t0 + row) * GLA_PP + 2048 + h * 512 + ch * 8); }
	ds_write_b128 v66, v[14:17] offset:34816
	v_lshl_add_u64 v[14:15], s[60:61], 0, v[68:69]
	v_lshlrev_b64 v[18:19], 11, v[14:15]
	v_lshl_add_u64 v[14:15], v[4:5], 0, v[18:19]
	v_mov_b64_e32 v[14:15], v[200:201]
	v_mov_b64_e32 v[16:17], v[202:203]
	s_waitcnt vmcnt(0)
	v_lshlrev_b32_e32 v20, 16, v14
	v_and_b32_e32 v21, 0xffff0000, v14
	v_pk_mul_f32 v[20:21], v[6:7], v[20:21]
	s_nop 0
	v_cvt_pk_bf16_f32 v14, v20, v21
	v_lshlrev_b32_e32 v20, 16, v15
	v_and_b32_e32 v21, 0xffff0000, v15
	v_pk_mul_f32 v[20:21], v[8:9], v[20:21]
	s_nop 0
	v_cvt_pk_bf16_f32 v15, v20, v21
	v_lshlrev_b32_e32 v20, 16, v16
	v_and_b32_e32 v21, 0xffff0000, v16
	v_pk_mul_f32 v[20:21], v[10:11], v[20:21]
	s_nop 0
	v_cvt_pk_bf16_f32 v16, v20, v21
	v_lshlrev_b32_e32 v20, 16, v17
	v_and_b32_e32 v21, 0xffff0000, v17
	v_pk_mul_f32 v[20:21], v[12:13], v[20:21]
	s_nop 0
	v_cvt_pk_bf16_f32 v17, v20, v21
	ds_write_b128 v70, v[14:17]
	v_lshl_add_u64 v[14:15], v[2:3], 0, v[18:19]
	v_mov_b64_e32 v[14:15], v[216:217]
	v_mov_b64_e32 v[16:17], v[218:219]
	s_waitcnt vmcnt(0)
	ds_write_b128 v70, v[14:17] offset:34816
	v_lshl_add_u64 v[14:15], s[60:61], 0, v[72:73]
	v_lshlrev_b64 v[18:19], 11, v[14:15]
	v_lshl_add_u64 v[14:15], v[4:5], 0, v[18:19]
	v_mov_b64_e32 v[14:15], v[204:205]
	v_mov_b64_e32 v[16:17], v[206:207]
	s_waitcnt vmcnt(0)
	v_lshlrev_b32_e32 v20, 16, v14
	v_and_b32_e32 v21, 0xffff0000, v14
	v_pk_mul_f32 v[20:21], v[6:7], v[20:21]
	s_nop 0
	v_cvt_pk_bf16_f32 v14, v20, v21
	v_lshlrev_b32_e32 v20, 16, v15
	v_and_b32_e32 v21, 0xffff0000, v15
	v_pk_mul_f32 v[20:21], v[8:9], v[20:21]
	s_nop 0
	v_cvt_pk_bf16_f32 v15, v20, v21
	v_lshlrev_b32_e32 v20, 16, v16
	v_and_b32_e32 v21, 0xffff0000, v16
	v_pk_mul_f32 v[20:21], v[10:11], v[20:21]
	s_nop 0
	v_cvt_pk_bf16_f32 v16, v20, v21
	v_lshlrev_b32_e32 v20, 16, v17
	v_and_b32_e32 v21, 0xffff0000, v17
	v_pk_mul_f32 v[20:21], v[12:13], v[20:21]
	s_nop 0
	v_cvt_pk_bf16_f32 v17, v20, v21
	ds_write_b128 v74, v[14:17]
	v_lshl_add_u64 v[14:15], v[2:3], 0, v[18:19]
	v_mov_b64_e32 v[14:15], v[220:221]
	v_mov_b64_e32 v[16:17], v[222:223]
	s_waitcnt vmcnt(0)
	ds_write_b128 v74, v[14:17] offset:34816
	v_lshl_add_u64 v[14:15], s[60:61], 0, v[76:77]
	v_lshlrev_b64 v[18:19], 11, v[14:15]
	v_lshl_add_u64 v[4:5], v[4:5], 0, v[18:19]
	v_mov_b64_e32 v[14:15], v[208:209]
	v_mov_b64_e32 v[16:17], v[210:211]
	v_lshl_add_u64 v[2:3], v[2:3], 0, v[18:19]
	s_waitcnt vmcnt(0)
	v_lshlrev_b32_e32 v4, 16, v14
	v_and_b32_e32 v5, 0xffff0000, v14
	v_pk_mul_f32 v[4:5], v[6:7], v[4:5]
	v_lshlrev_b32_e32 v6, 16, v15
	v_and_b32_e32 v7, 0xffff0000, v15
	v_pk_mul_f32 v[6:7], v[8:9], v[6:7]
	v_cvt_pk_bf16_f32 v4, v4, v5
	v_cvt_pk_bf16_f32 v5, v6, v7
	v_lshlrev_b32_e32 v6, 16, v16
	v_and_b32_e32 v7, 0xffff0000, v16
	v_lshlrev_b32_e32 v8, 16, v17
	v_and_b32_e32 v9, 0xffff0000, v17
	v_pk_mul_f32 v[6:7], v[10:11], v[6:7]
	v_pk_mul_f32 v[8:9], v[12:13], v[8:9]
	v_cvt_pk_bf16_f32 v6, v6, v7
	v_cvt_pk_bf16_f32 v7, v8, v9
	ds_write_b128 v78, v[4:7]
	v_mov_b64_e32 v[2:3], v[224:225]
	v_mov_b64_e32 v[4:5], v[226:227]
	v_mov_b64_e32 v[6:7], s[74:75]
	s_waitcnt vmcnt(0)
	ds_write_b128 v78, v[2:5] offset:34816
	v_lshl_add_u64 v[2:3], s[60:61], 0, v[80:81]
	v_mad_u64_u32 v[4:5], s[34:35], v2, s28, v[6:7]
	v_mad_i32_i24 v5, v3, s28, v5
	v_lshl_add_u64 v[2:3], v[4:5], 0, s[0:1]
	v_lshl_add_u64 v[2:3], v[2:3], 0, v[0:1]
	v_add_co_u32_e32 v2, vcc, s21, v2
	s_nop 1
	v_addc_co_u32_e32 v3, vcc, 0, v3, vcc
	v_mov_b64_e32 v[2:3], v[228:229]
	v_mov_b64_e32 v[4:5], v[230:231]
	s_waitcnt vmcnt(0)
	ds_write_b128 v99, v[2:5]
	v_lshl_add_u64 v[2:3], s[60:61], 0, v[82:83]
	v_mad_u64_u32 v[4:5], s[34:35], v2, s28, v[6:7]
	v_mad_i32_i24 v5, v3, s28, v5
	v_lshl_add_u64 v[2:3], v[4:5], 0, s[0:1]
	v_lshl_add_u64 v[2:3], v[2:3], 0, v[0:1]
	v_add_co_u32_e32 v2, vcc, s21, v2
	s_nop 1
	v_addc_co_u32_e32 v3, vcc, 0, v3, vcc
	v_mov_b64_e32 v[2:3], v[232:233]
	v_mov_b64_e32 v[4:5], v[234:235]
	s_waitcnt vmcnt(0)
	ds_write_b128 v101, v[2:5]
	v_lshl_add_u64 v[2:3], s[60:61], 0, v[84:85]
	v_mad_u64_u32 v[4:5], s[34:35], v2, s28, v[6:7]
	v_mad_i32_i24 v5, v3, s28, v5
	v_lshl_add_u64 v[2:3], v[4:5], 0, s[0:1]
	v_lshl_add_u64 v[2:3], v[2:3], 0, v[0:1]
	v_add_co_u32_e32 v2, vcc, s21, v2
	s_nop 1
	v_addc_co_u32_e32 v3, vcc, 0, v3, vcc
	v_mov_b64_e32 v[2:3], v[236:237]
	v_mov_b64_e32 v[4:5], v[238:239]
	s_waitcnt vmcnt(0)
	ds_write_b128 v134, v[2:5]
	v_lshl_add_u64 v[2:3], s[60:61], 0, v[86:87]
	v_mad_u64_u32 v[4:5], s[34:35], v2, s28, v[6:7]
	v_mad_i32_i24 v5, v3, s28, v5
	v_lshl_add_u64 v[2:3], v[4:5], 0, s[0:1]
	v_lshl_add_u64 v[2:3], v[2:3], 0, v[0:1]
	v_add_co_u32_e32 v2, vcc, s21, v2
	s_nop 1
	v_addc_co_u32_e32 v3, vcc, 0, v3, vcc
	v_mov_b64_e32 v[2:3], v[240:241]
	v_mov_b64_e32 v[4:5], v[242:243]
	s_waitcnt vmcnt(0)
	ds_write_b128 v135, v[2:5]
	v_lshl_add_u64 v[2:3], s[60:61], 0, v[88:89]
	v_mad_u64_u32 v[4:5], s[34:35], v2, s28, v[6:7]
	v_mad_i32_i24 v5, v3, s28, v5
	v_lshl_add_u64 v[2:3], v[4:5], 0, s[0:1]
	v_lshl_add_u64 v[2:3], v[2:3], 0, v[0:1]
	v_add_co_u32_e32 v2, vcc, s21, v2
	s_nop 1
	v_addc_co_u32_e32 v3, vcc, 0, v3, vcc
	v_mov_b64_e32 v[2:3], v[244:245]
	v_mov_b64_e32 v[4:5], v[246:247]
	s_waitcnt vmcnt(0)
	ds_write_b128 v136, v[2:5]
	v_lshl_add_u64 v[2:3], s[60:61], 0, v[90:91]
	v_mad_u64_u32 v[4:5], s[34:35], v2, s28, v[6:7]
	v_mad_i32_i24 v5, v3, s28, v5
	v_lshl_add_u64 v[2:3], v[4:5], 0, s[0:1]
	v_lshl_add_u64 v[2:3], v[2:3], 0, v[0:1]
	v_add_co_u32_e32 v2, vcc, s21, v2
	s_nop 1
	v_addc_co_u32_e32 v3, vcc, 0, v3, vcc
	v_mov_b64_e32 v[2:3], v[248:249]
	v_mov_b64_e32 v[4:5], v[250:251]
	s_waitcnt vmcnt(0)
	ds_write_b128 v137, v[2:5]
	v_lshl_add_u64 v[2:3], s[60:61], 0, v[92:93]
	v_mad_u64_u32 v[4:5], s[34:35], v2, s28, v[6:7]
	v_mad_i32_i24 v5, v3, s28, v5
	v_lshl_add_u64 v[2:3], v[4:5], 0, s[0:1]
	v_lshl_add_u64 v[2:3], v[2:3], 0, v[0:1]
	v_add_co_u32_e32 v2, vcc, s21, v2
	s_nop 1
	v_addc_co_u32_e32 v3, vcc, 0, v3, vcc
	global_load_dwordx4 v[2:5], v[2:3], off
	s_waitcnt vmcnt(0)
	ds_write_b128 v138, v[2:5]
	v_lshl_add_u64 v[2:3], s[60:61], 0, v[94:95]
	v_mad_u64_u32 v[4:5], s[34:35], v2, s28, v[6:7]
	v_mad_i32_i24 v5, v3, s28, v5
	v_lshl_add_u64 v[2:3], v[4:5], 0, s[0:1]
	v_lshl_add_u64 v[2:3], v[2:3], 0, v[0:1]
	v_add_co_u32_e32 v2, vcc, s21, v2
	s_lshl_b32 s0, s20, 4
	s_nop 0
	v_addc_co_u32_e32 v3, vcc, 0, v3, vcc
	global_load_dwordx4 v[2:5], v[2:3], off
	s_add_u32 s0, s0, s64
	s_addc_u32 s1, 0, s65
	s_add_u32 s0, s0, s60
	s_addc_u32 s1, s1, s61
	s_lshl_b64 s[0:1], s[0:1], 12
	s_waitcnt vmcnt(0)
	ds_write_b128 v139, v[2:5]
	s_waitcnt lgkmcnt(0)
	s_barrier
; #define LAS __attribute__((address_space(3)))
; __device__ __forceinline__ unsigned cvtpk(float lo, float hi) { return pg8::cvt_pk_bf16(lo, hi); }
; __device__ __forceinline__ f32x4 mma16(bf16x8 a, bf16x8 b, f32x4 c) { return __builtin_amdgcn_mfma_f32_16x16x32_bf16(a, b, c, 0, 0, 0); }
; __device__ __forceinline__ void gla_post_phase(LAS unsigned char* lds, const bf16_t* QT, const bf16_t* KT  , const float* DEC, const bf16_t* proj, const bf16_t* OI, const float* gnorm, bf16_t* OG, int wg, int nwg, int tid) {
;     ...
;         {
;             const int st_ = wave >> 1;
; #pragma unroll
;             for (int e = 0; e < 2; ++e) { const int tt = 2 * (wave & 1) + e; f32x4 acc = (f32x4){0.f, 0.f, 0.f, 0.f};
; #pragma unroll
;                 for (int ks = 0; ks < 8; ++ks) acc = mma16(frag_rowk(Kt, QP, 16 * st_, 32 * ks, fr, fq), frag_rowk(Qt, QP, 16 * tt, 32 * ks, fr, fq), acc);
;                 const int t = 16 * tt + fr, s0 = 16 * st_ + 4 * fq;
;                 u32x2 w; w.x = cvtpk(s0 <= t ? acc[0] : 0.f, s0 + 1 <= t ? acc[1] : 0.f); w.y = cvtpk(s0 + 2 <= t ? acc[2] : 0.f, s0 + 3 <= t ? acc[3] : 0.f);
;                 *(LAS u32x2*)(P + t * PP + 32 * (st_ >> 1) + 8 * fq + 4 * (st_ & 1)) = w; }
;         }
;         __syncthreads();
	ds_read_b128 v[2:5], v140 offset:34816
	ds_read_b128 v[6:9], v141
	s_waitcnt lgkmcnt(0)
	v_mfma_f32_16x16x32_bf16 v[2:5], v[2:5], v[6:9], 0
	ds_read_b128 v[6:9], v140 offset:34880
	ds_read_b128 v[10:13], v141 offset:64
	s_waitcnt lgkmcnt(0)
	v_mfma_f32_16x16x32_bf16 v[2:5], v[6:9], v[10:13], v[2:5]
	ds_read_b128 v[6:9], v140 offset:34944
	ds_read_b128 v[10:13], v141 offset:128
	s_waitcnt lgkmcnt(0)
	v_mfma_f32_16x16x32_bf16 v[2:5], v[6:9], v[10:13], v[2:5]
	ds_read_b128 v[6:9], v140 offset:35008
	ds_read_b128 v[10:13], v141 offset:192
	s_waitcnt lgkmcnt(0)
	v_mfma_f32_16x16x32_bf16 v[2:5], v[6:9], v[10:13], v[2:5]
	ds_read_b128 v[6:9], v140 offset:35072
	ds_read_b128 v[10:13], v141 offset:256
	s_waitcnt lgkmcnt(0)
	v_mfma_f32_16x16x32_bf16 v[2:5], v[6:9], v[10:13], v[2:5]
	ds_read_b128 v[6:9], v140 offset:35136
	ds_read_b128 v[10:13], v141 offset:320
	s_waitcnt lgkmcnt(0)
	v_mfma_f32_16x16x32_bf16 v[2:5], v[6:9], v[10:13], v[2:5]
	ds_read_b128 v[6:9], v140 offset:35200
	ds_read_b128 v[10:13], v141 offset:384
	s_waitcnt lgkmcnt(0)
	v_mfma_f32_16x16x32_bf16 v[2:5], v[6:9], v[10:13], v[2:5]
	ds_read_b128 v[6:9], v140 offset:35264
	ds_read_b128 v[10:13], v141 offset:448
	s_waitcnt lgkmcnt(0)
	v_mfma_f32_16x16x32_bf16 v[2:5], v[6:9], v[10:13], v[2:5]
	s_nop 7
	v_cndmask_b32_e64 v2, v2, 0, s[42:43]
	v_cndmask_b32_e64 v3, 0, v3, s[44:45]
	v_cvt_pk_bf16_f32 v2, v2, v3
	v_cndmask_b32_e64 v3, v4, 0, s[46:47]
	v_cndmask_b32_e64 v4, v5, 0, s[48:49]
	v_cvt_pk_bf16_f32 v3, v3, v4
	ds_write_b64 v142, v[2:3]
	ds_read_b128 v[2:5], v140 offset:34816
	ds_read_b128 v[6:9], v141 offset:8704
	s_waitcnt lgkmcnt(0)
	v_mfma_f32_16x16x32_bf16 v[2:5], v[2:5], v[6:9], 0
	ds_read_b128 v[6:9], v140 offset:34880
	ds_read_b128 v[10:13], v141 offset:8768
	s_waitcnt lgkmcnt(0)
	v_mfma_f32_16x16x32_bf16 v[2:5], v[6:9], v[10:13], v[2:5]
	ds_read_b128 v[6:9], v140 offset:34944
	ds_read_b128 v[10:13], v141 offset:8832
	s_waitcnt lgkmcnt(0)
	v_mfma_f32_16x16x32_bf16 v[2:5], v[6:9], v[10:13], v[2:5]
	ds_read_b128 v[6:9], v140 offset:35008
	ds_read_b128 v[10:13], v141 offset:8896
	s_waitcnt lgkmcnt(0)
	v_mfma_f32_16x16x32_bf16 v[2:5], v[6:9], v[10:13], v[2:5]
	ds_read_b128 v[6:9], v140 offset:35072
	ds_read_b128 v[10:13], v141 offset:8960
	s_waitcnt lgkmcnt(0)
	v_mfma_f32_16x16x32_bf16 v[2:5], v[6:9], v[10:13], v[2:5]
	ds_read_b128 v[6:9], v140 offset:35136
	ds_read_b128 v[10:13], v141 offset:9024
	s_waitcnt lgkmcnt(0)
	v_mfma_f32_16x16x32_bf16 v[2:5], v[6:9], v[10:13], v[2:5]
	ds_read_b128 v[6:9], v140 offset:35200
	ds_read_b128 v[10:13], v141 offset:9088
	s_waitcnt lgkmcnt(0)
	v_mfma_f32_16x16x32_bf16 v[2:5], v[6:9], v[10:13], v[2:5]
	ds_read_b128 v[6:9], v140 offset:35264
	ds_read_b128 v[10:13], v141 offset:9152
	s_waitcnt lgkmcnt(0)
	v_mfma_f32_16x16x32_bf16 v[2:5], v[6:9], v[10:13], v[2:5]
	s_nop 7
	v_cndmask_b32_e64 v2, v2, 0, s[50:51]
	v_cndmask_b32_e64 v3, 0, v3, s[52:53]
	v_cvt_pk_bf16_f32 v2, v2, v3
	v_cndmask_b32_e64 v3, v4, 0, s[54:55]
	v_cndmask_b32_e64 v4, v5, 0, s[56:57]
	v_cvt_pk_bf16_f32 v3, v3, v4
	ds_write_b64 v142, v[2:3] offset:2560
	s_waitcnt lgkmcnt(0)
	s_barrier
; #define LAS __attribute__((address_space(3)))
; __device__ __forceinline__ float bflo(unsigned u) { return __uint_as_float(u << 16); }
; __device__ __forceinline__ void gla_post_phase(LAS unsigned char* lds, const bf16_t* QT, const bf16_t* KT  , const float* DEC, const bf16_t* proj, const bf16_t* OI, const float* gnorm, bf16_t* OG, int wg, int nwg, int tid) {
;     ...
;         f32x4 acc[4][4];
; #pragma unroll
;         for (int vt = 0; vt < 4; ++vt)
; #pragma unroll
;             for (int tt = 0; tt < 4; ++tt) acc[vt][tt] = (f32x4){0.f, 0.f, 0.f, 0.f};
; #pragma unroll
;         for (int ks = 0; ks < 2; ++ks) {
;             bf16x8 pb[4];
; #pragma unroll
;             for (int tt = 0; tt < 4; ++tt) pb[tt] = frag_rowk(P, PP, 16 * tt, 32 * ks, fr, fq);
; #pragma unroll
;             for (int vt = 0; vt < 4; ++vt) { const int cb = 64 * wave + 32 * (vt >> 1) + 8 * (fr & 3) + 4 * (vt & 1);
;                 const LAS bf16_t* pa = V + (32 * ks + 4 * fq + (fr >> 2)) * VP + cb;
;                 const s16x4 ta = __builtin_amdgcn_ds_read_tr16_b64_v4i16((LAS s16x4*)pa), tb2 = __builtin_amdgcn_ds_read_tr16_b64_v4i16((LAS s16x4*)(pa + 16 * VP));
;                 const bf16x8 af = (bf16x8){ta[0], ta[1], ta[2], ta[3], tb2[0], tb2[1], tb2[2], tb2[3]};
; #pragma unroll
;                 for (int tt = 0; tt < 4; ++tt) acc[vt][tt] = mma16(af, pb[tt], acc[vt][tt]); }
;         }
;         float ss[4];
; #pragma unroll
;         for (int tt = 0; tt < 4; ++tt) { ss[tt] = 0.f;
; #pragma unroll
;             for (int P2 = 0; P2 < 2; ++P2) { const u32x4 oiw = *(const u32x4*)(OI + (((size_t)bc * 4 + h) * 16 + 2 * wave + P2) * 2048 + (16 * tt + fr) * 32 + 8 * fq);
;                 const f32x4 o0 = (f32x4){bflo(oiw.x), bfhi(oiw.x), bflo(oiw.y), bfhi(oiw.y)}, o1 = (f32x4){bflo(oiw.z), bfhi(oiw.z), bflo(oiw.w), bfhi(oiw.w)};
;                 acc[2 * P2][tt] = acc[2 * P2][tt] + o0; acc[2 * P2 + 1][tt] = acc[2 * P2 + 1][tt] + o1;
;                 const f32x4 a = acc[2 * P2][tt], c = acc[2 * P2 + 1][tt];
;                 ss[tt] += ((a[0] * a[0] + a[1] * a[1]) + (a[2] * a[2] + a[3] * a[3])) + ((c[0] * c[0] + c[1] * c[1]) + (c[2] * c[2] + c[3] * c[3])); }
;             ss[tt] += __shfl_xor(ss[tt], 16); ss[tt] += __shfl_xor(ss[tt], 32);
;             if (fq == 0) red[(16 * tt + fr) * 8 + wave] = ss[tt]; }
	ds_read_b128 v[2:5], v143
	ds_read_b128 v[6:9], v143 offset:2560
	ds_read_b128 v[10:13], v143 offset:5120
	ds_read_b128 v[14:17], v143 offset:7680
	ds_read_b64_tr_b16 v[20:21], v79 offset:16896
	ds_read_b64_tr_b16 v[18:19], v79
	ds_read_b64_tr_b16 v[22:23], v79 offset:8
	ds_read_b64_tr_b16 v[24:25], v79 offset:16904
	ds_read_b64_tr_b16 v[42:43], v79 offset:64
	ds_read_b64_tr_b16 v[44:45], v79 offset:16960
	s_waitcnt lgkmcnt(0)
	v_mfma_f32_16x16x32_bf16 v[54:57], v[42:45], v[2:5], 0
	v_mfma_f32_16x16x32_bf16 v[114:117], v[42:45], v[6:9], 0
	v_mfma_f32_16x16x32_bf16 v[118:121], v[42:45], v[10:13], 0
	v_mfma_f32_16x16x32_bf16 v[122:125], v[42:45], v[14:17], 0
	ds_read_b64_tr_b16 v[42:43], v79 offset:72
	ds_read_b64_tr_b16 v[44:45], v79 offset:16968
	v_mfma_f32_16x16x32_bf16 v[26:29], v[18:21], v[2:5], 0
	v_mfma_f32_16x16x32_bf16 v[38:41], v[22:25], v[2:5], 0
	s_waitcnt lgkmcnt(0)
	v_mfma_f32_16x16x32_bf16 v[126:129], v[42:45], v[2:5], 0
	ds_read_b128 v[152:155], v143 offset:64
	ds_read_b128 v[156:159], v143 offset:2624
	ds_read_b128 v[160:163], v143 offset:5184
	ds_read_b128 v[168:171], v143 offset:7744
	ds_read_b64_tr_b16 v[2:3], v79 offset:33792
	ds_read_b64_tr_b16 v[4:5], v79 offset:50688
	v_mfma_f32_16x16x32_bf16 v[30:33], v[18:21], v[6:9], 0
	v_mfma_f32_16x16x32_bf16 v[34:37], v[18:21], v[10:13], 0
	v_mfma_f32_16x16x32_bf16 v[18:21], v[18:21], v[14:17], 0
	v_mfma_f32_16x16x32_bf16 v[46:49], v[22:25], v[6:9], 0
	v_mfma_f32_16x16x32_bf16 v[50:53], v[22:25], v[10:13], 0
	v_mfma_f32_16x16x32_bf16 v[6:9], v[42:45], v[6:9], 0
	v_mfma_f32_16x16x32_bf16 v[130:133], v[42:45], v[10:13], 0
	v_mfma_f32_16x16x32_bf16 v[148:151], v[42:45], v[14:17], 0
	s_waitcnt lgkmcnt(0)
	v_mfma_f32_16x16x32_bf16 v[176:179], v[2:5], v[152:155], v[26:29]
	v_mfma_f32_16x16x32_bf16 v[42:45], v[2:5], v[156:159], v[30:33]
	v_mfma_f32_16x16x32_bf16 v[26:29], v[2:5], v[160:163], v[34:37]
	v_mfma_f32_16x16x32_bf16 v[10:13], v[2:5], v[168:171], v[18:21]
	ds_read_b64_tr_b16 v[2:3], v79 offset:33800
	ds_read_b64_tr_b16 v[4:5], v79 offset:50696
	v_mfma_f32_16x16x32_bf16 v[22:25], v[22:25], v[14:17], 0
	s_waitcnt lgkmcnt(0)
	v_mfma_f32_16x16x32_bf16 v[180:183], v[2:5], v[152:155], v[38:41]
	v_mfma_f32_16x16x32_bf16 v[46:49], v[2:5], v[156:159], v[46:49]
	v_mfma_f32_16x16x32_bf16 v[30:33], v[2:5], v[160:163], v[50:53]
	v_mfma_f32_16x16x32_bf16 v[14:17], v[2:5], v[168:171], v[22:25]
	ds_read_b64_tr_b16 v[2:3], v79 offset:33856
	ds_read_b64_tr_b16 v[4:5], v79 offset:50752
	s_waitcnt lgkmcnt(0)
	v_mfma_f32_16x16x32_bf16 v[34:37], v[2:5], v[156:159], v[114:117]
	s_nop 2
	ds_read_b64_tr_b16 v[114:115], v79 offset:33864
	ds_read_b64_tr_b16 v[116:117], v79 offset:50760
	s_waitcnt lgkmcnt(0)
	v_mfma_f32_16x16x32_bf16 v[22:25], v[114:117], v[160:163], v[130:133]
	s_nop 2
	v_lshl_add_u64 v[132:133], v[102:103], 0, s[0:1]
	s_bitset1_b32 s0, 12
	v_mfma_f32_16x16x32_bf16 v[50:53], v[2:5], v[152:155], v[54:57]
	v_mfma_f32_16x16x32_bf16 v[54:57], v[114:117], v[152:155], v[126:129]
	v_mfma_f32_16x16x32_bf16 v[38:41], v[114:117], v[156:159], v[6:9]
	v_mfma_f32_16x16x32_bf16 v[6:9], v[114:117], v[168:171], v[148:151]
	global_load_dwordx4 v[114:117], v[132:133], off
	v_mfma_f32_16x16x32_bf16 v[18:21], v[2:5], v[160:163], v[118:121]
	v_mfma_f32_16x16x32_bf16 v[2:5], v[2:5], v[168:171], v[122:125]
	s_waitcnt vmcnt(0)
	s_nop 0
	v_lshlrev_b32_e32 v118, 16, v114
	v_and_b32_e32 v119, 0xffff0000, v114
	v_lshlrev_b32_e32 v114, 16, v115
	v_and_b32_e32 v115, 0xffff0000, v115
	v_pk_add_f32 v[128:129], v[178:179], v[114:115]
	v_pk_add_f32 v[130:131], v[176:177], v[118:119]
	v_lshlrev_b32_e32 v120, 16, v116
	v_and_b32_e32 v121, 0xffff0000, v116
	v_lshlrev_b32_e32 v116, 16, v117
	v_and_b32_e32 v117, 0xffff0000, v117
	v_mul_f32_e32 v114, v131, v131
	v_mul_f32_e32 v115, v129, v129
	v_pk_add_f32 v[124:125], v[182:183], v[116:117]
	v_pk_add_f32 v[126:127], v[180:181], v[120:121]
	v_fmac_f32_e32 v114, v130, v130
	v_fmac_f32_e32 v115, v128, v128
	v_add_f32_e32 v114, v114, v115
	v_mul_f32_e32 v115, v127, v127
	v_mul_f32_e32 v116, v125, v125
	v_fmac_f32_e32 v115, v126, v126
	v_fmac_f32_e32 v116, v124, v124
	v_add_f32_e32 v115, v115, v116
	v_add_f32_e32 v147, v114, v115
	v_lshl_add_u64 v[114:115], v[102:103], 0, s[0:1]
	global_load_dwordx4 v[114:117], v[114:115], off
	s_waitcnt vmcnt(0)
	v_lshlrev_b32_e32 v118, 16, v114
	v_and_b32_e32 v119, 0xffff0000, v114
	v_lshlrev_b32_e32 v114, 16, v115
	v_and_b32_e32 v115, 0xffff0000, v115
	v_pk_add_f32 v[120:121], v[52:53], v[114:115]
	v_pk_add_f32 v[122:123], v[50:51], v[118:119]
	v_lshlrev_b32_e32 v148, 16, v116
	v_and_b32_e32 v149, 0xffff0000, v116
	v_lshlrev_b32_e32 v116, 16, v117
	v_and_b32_e32 v117, 0xffff0000, v117
	v_mul_f32_e32 v50, v123, v123
	v_mul_f32_e32 v51, v121, v121
	v_pk_add_f32 v[116:117], v[56:57], v[116:117]
	v_pk_add_f32 v[118:119], v[54:55], v[148:149]
	v_fmac_f32_e32 v50, v122, v122
	v_fmac_f32_e32 v51, v120, v120
	v_add_f32_e32 v50, v50, v51
	v_mul_f32_e32 v51, v119, v119
	v_mul_f32_e32 v52, v117, v117
	v_fmac_f32_e32 v51, v118, v118
	v_fmac_f32_e32 v52, v116, v116
	v_add_f32_e32 v51, v51, v52
	v_add_f32_e32 v50, v50, v51
	v_add_f32_e32 v50, v147, v50
	ds_bpermute_b32 v51, v67, v50
	s_waitcnt lgkmcnt(0)
	v_add_f32_e32 v50, v50, v51
	ds_bpermute_b32 v51, v71, v50
	s_and_saveexec_b64 s[20:21], s[36:37]
	s_cbranch_execz .LBB0_929
	s_waitcnt lgkmcnt(0)
	v_add_f32_e32 v50, v50, v51
	ds_write_b32 v75, v50
